# combo28 + forward substitution: waves 0..3 (all eight row blocks) at raised issue priority over the waves sharing their SIMDs
# baseline (speedup 1.0000x reference)
; #define LAS __attribute__((address_space(3)))
; __device__ __forceinline__ bf16_t f2bf(float f) { return (bf16_t)(cvt_pk_bf16(f, 0.f) & 0xffffu); }
; __device__ __forceinline__ void dn_prep(const Params& p, LAS unsigned char* lds) {
;     ...
;         if (wid == 0) {
;             float T[64];
;             int zoff; asm volatile("v_mov_b32 %0, 0" : "=v"(zoff));
;             const LAS float* Asz = As + zoff;
;             const float bc = beta_s[lane], wcf = bc * __expf(G_s[lane]);
;             int lo2 = lane; asm volatile("" : "+v"(lo2));
;             LAS bf16_t* tub = Tu + lo2; LAS bf16_t* twb = Tw + lo2;
;             f32x4 rlo[2][8], rhi[8];
;             T[0] = (lane == 0) ? 1.f : 0.f;
;             tub[0] = f2bf(T[0] * bc); twb[0] = f2bf(T[0] * wcf);
;             rlo[1][0] = *(const LAS f32x4*)(Asz + 68);
.LBB0_375:
	s_or_b64 exec, exec, s[24:25]
	s_waitcnt lgkmcnt(0)
	s_barrier
	s_and_b64 s[0:1], s[2:3], s[68:69]
	s_xor_b64 s[0:1], s[0:1], -1
	s_and_saveexec_b64 s[6:7], s[0:1]
	s_xor_b64 s[24:25], exec, s[6:7]
	s_cbranch_execz .LBB0_379
	s_mov_b64 s[28:29], exec
	s_and_b64 vcc, exec, s[68:69]
	s_cbranch_vccnz .LBB0_378
	v_readfirstlane_b32 s1, v184
	v_and_b32_e32 v7, 63, v184
	s_nop 3
	s_lshr_b32 s1, s1, 6
	v_and_b32_e32 v6, 7, v7
	v_lshrrev_b32_e32 v7, 3, v7
	s_lshl_b32 s32, s1, 3
	s_cmp_lt_u32 s1, 4
	s_cbranch_scc0 .Lfs_noprio
	s_setprio 2
.Lfs_noprio:
	s_movk_i32 s89, 0x90
	s_mov_b32 s6, 0x02020202
	s_mov_b32 s7, 0x02020202
	s_mov_b32 s68, 0x04040404
	s_mov_b32 s69, 0x04040404
	s_mov_b32 s92, 0x08080808
	s_mov_b32 s93, 0x08080808
	s_mov_b32 s94, 0x10101010
	s_mov_b32 s95, 0x10101010
	s_mov_b32 s96, 0x20202020
	s_mov_b32 s97, 0x20202020
	s_mov_b32 s98, 0x40404040
	s_mov_b32 s99, 0x40404040
	s_mov_b32 s100, 0x80808080
	s_mov_b32 s101, 0x80808080
	v_add_u32_e32 v128, s32, v7
	v_cmp_eq_u32_e32 vcc, 0, v7
	s_nop 1
	v_cndmask_b32_e64 v16, 0, 1.0, vcc
	v_cmp_eq_u32_e32 vcc, 1, v7
	s_nop 1
	v_cndmask_b32_e64 v17, 0, 1.0, vcc
	v_cmp_eq_u32_e32 vcc, 2, v7
	s_nop 1
	v_cndmask_b32_e64 v18, 0, 1.0, vcc
	v_cmp_eq_u32_e32 vcc, 3, v7
	s_nop 1
	v_cndmask_b32_e64 v19, 0, 1.0, vcc
	v_cmp_eq_u32_e32 vcc, 4, v7
	s_nop 1
	v_cndmask_b32_e64 v20, 0, 1.0, vcc
	v_cmp_eq_u32_e32 vcc, 5, v7
	s_nop 1
	v_cndmask_b32_e64 v21, 0, 1.0, vcc
	v_cmp_eq_u32_e32 vcc, 6, v7
	s_nop 1
	v_cndmask_b32_e64 v22, 0, 1.0, vcc
	v_cmp_eq_u32_e32 vcc, 7, v7
	s_nop 1
	v_cndmask_b32_e64 v23, 0, 1.0, vcc
	v_lshl_add_u32 v0, v6, 2, s13
	v_mov_b32_e32 v1, s13
	v_mov_b32_e32 v40, 0x110
	v_mad_u32_u24 v40, v6, v40, v1
	v_lshlrev_b32_e32 v2, 1, v128
	v_mad_u32_u24 v2, v6, s89, v2
	v_add_u32_e32 v3, 0x18000, v2
	v_add_u32_e32 v2, 0x15c00, v2
	v_lshlrev_b32_e32 v129, 2, v128
	v_add_u32_e32 v129, 0x1a400, v129
	ds_read_b32 v4, v129
	ds_read_b32 v5, v129 offset:256
	ds_read_b128 v[32:35], v40 offset:0
	ds_read_b128 v[36:39], v40 offset:16
	v_mov_b32_e32 v8, 0
	v_mov_b32_e32 v9, 0
	v_mov_b32_e32 v10, 0
	v_mov_b32_e32 v11, 0
	v_mov_b32_e32 v12, 0
	v_mov_b32_e32 v13, 0
	v_mov_b32_e32 v14, 0
	v_mov_b32_e32 v15, 0
	v_mov_b32_e32 v6, 0
	s_mov_b32 s91, 1.0
	s_waitcnt lgkmcnt(2)
	v_mul_f32_e32 v5, 0x3fb8aa3b, v5
	v_exp_f32_e32 v5, v5
	s_nop 0
	v_mul_f32_e32 v5, v4, v5

; #define LAS __attribute__((address_space(3)))
; __device__ __forceinline__ bf16_t f2bf(float f) { return (bf16_t)(cvt_pk_bf16(f, 0.f) & 0xffffu); }
; __device__ __forceinline__ void dn_prep(const Params& p, LAS unsigned char* lds) {
;     ...
;             for (int i = 1; i < 64; ++i) {
; #pragma unroll
;                 for (int j4 = 8; j4 < (i + 3) / 4; ++j4) rhi[j4 - 8] = *(const LAS f32x4*)(Asz + i * 68 + j4 * 4);
;                 if (i + 1 < 64) {
; #pragma unroll
;                     for (int j4 = 0; j4 < ((i + 4) / 4 < 8 ? (i + 4) / 4 : 8); ++j4) rlo[(i + 1) & 1][j4] = *(const LAS f32x4*)(Asz + (i + 1) * 68 + j4 * 4);
;                 }
;                 float a0 = (lane == i) ? 1.f : 0.f, a1 = 0.f, a2 = 0.f, a3 = 0.f;
; #pragma unroll
;                 for (int j4 = 0; j4 < (i + 3) / 4; ++j4) {
;                     const f32x4 av = (j4 < 8) ? rlo[i & 1][j4 & 7] : rhi[(j4 - 8) & 7];
;                     if (j4 * 4 + 0 < i) a0 -= av[0] * T[j4 * 4 + 0];
;                     if (j4 * 4 + 1 < i) a1 -= av[1] * T[j4 * 4 + 1];
;                     if (j4 * 4 + 2 < i) a2 -= av[2] * T[j4 * 4 + 2];
;                     if (j4 * 4 + 3 < i) a3 -= av[3] * T[j4 * 4 + 3];
;                 }
;                 T[i] = (a0 + a1) + (a2 + a3);
;                 tub[i * 72] = f2bf(T[i] * bc); twb[i * 72] = f2bf(T[i] * wcf);
;                 __builtin_amdgcn_sched_barrier(0);
.Lfs_b7:
	s_waitcnt lgkmcnt(4)
	v_mul_f32_e32 v24, v72, v8
	v_mul_f32_e32 v25, v79, v8
	v_mul_f32_e32 v26, v86, v8
	v_mul_f32_e32 v27, v93, v8
	v_mul_f32_e32 v28, v100, v8
	v_mul_f32_e32 v29, v107, v8
	v_mul_f32_e32 v30, v114, v8
	v_mul_f32_e32 v31, v121, v8
	v_fmac_f32_e32 v24, v73, v9
	v_fmac_f32_e32 v25, v80, v9
	v_fmac_f32_e32 v26, v87, v9
	v_fmac_f32_e32 v27, v94, v9
	v_fmac_f32_e32 v28, v101, v9
	v_fmac_f32_e32 v29, v108, v9
	v_fmac_f32_e32 v30, v115, v9
	v_fmac_f32_e32 v31, v122, v9
	v_fmac_f32_e32 v24, v74, v10
	v_fmac_f32_e32 v25, v81, v10
	v_fmac_f32_e32 v26, v88, v10
	v_fmac_f32_e32 v27, v95, v10
	v_fmac_f32_e32 v28, v102, v10
	v_fmac_f32_e32 v29, v109, v10
	v_fmac_f32_e32 v30, v116, v10
	v_fmac_f32_e32 v31, v123, v10
	v_fmac_f32_e32 v24, v75, v11
	v_fmac_f32_e32 v25, v82, v11
	v_fmac_f32_e32 v26, v89, v11
	v_fmac_f32_e32 v27, v96, v11
	v_fmac_f32_e32 v28, v103, v11
	v_fmac_f32_e32 v29, v110, v11
	v_fmac_f32_e32 v30, v117, v11
	v_fmac_f32_e32 v31, v124, v11
	v_fmac_f32_e32 v24, v76, v12
	v_fmac_f32_e32 v25, v83, v12
	v_fmac_f32_e32 v26, v90, v12
	v_fmac_f32_e32 v27, v97, v12
	v_fmac_f32_e32 v28, v104, v12
	v_fmac_f32_e32 v29, v111, v12
	v_fmac_f32_e32 v30, v118, v12
	v_fmac_f32_e32 v31, v125, v12
	v_fmac_f32_e32 v24, v77, v13
	v_fmac_f32_e32 v25, v84, v13
	v_fmac_f32_e32 v26, v91, v13
	v_fmac_f32_e32 v27, v98, v13
	v_fmac_f32_e32 v28, v105, v13
	v_fmac_f32_e32 v29, v112, v13
	v_fmac_f32_e32 v30, v119, v13
	v_fmac_f32_e32 v31, v126, v13
	v_fmac_f32_e32 v24, v78, v14
	v_fmac_f32_e32 v25, v85, v14
	v_fmac_f32_e32 v26, v92, v14
	v_fmac_f32_e32 v27, v99, v14
	v_fmac_f32_e32 v28, v106, v14
	v_fmac_f32_e32 v29, v113, v14
	v_fmac_f32_e32 v30, v120, v14
	v_fmac_f32_e32 v31, v127, v14
	v_add_f32_dpp v24, v24, v24 quad_perm:[1,0,3,2] row_mask:0xf bank_mask:0xf bound_ctrl:1
	v_add_f32_dpp v25, v25, v25 quad_perm:[1,0,3,2] row_mask:0xf bank_mask:0xf bound_ctrl:1
	v_add_f32_dpp v26, v26, v26 quad_perm:[1,0,3,2] row_mask:0xf bank_mask:0xf bound_ctrl:1
	v_add_f32_dpp v27, v27, v27 quad_perm:[1,0,3,2] row_mask:0xf bank_mask:0xf bound_ctrl:1
	v_add_f32_dpp v28, v28, v28 quad_perm:[1,0,3,2] row_mask:0xf bank_mask:0xf bound_ctrl:1
	v_add_f32_dpp v29, v29, v29 quad_perm:[1,0,3,2] row_mask:0xf bank_mask:0xf bound_ctrl:1
	v_add_f32_dpp v30, v30, v30 quad_perm:[1,0,3,2] row_mask:0xf bank_mask:0xf bound_ctrl:1
	v_add_f32_dpp v31, v31, v31 quad_perm:[1,0,3,2] row_mask:0xf bank_mask:0xf bound_ctrl:1
	v_add_f32_dpp v24, v24, v24 quad_perm:[2,3,0,1] row_mask:0xf bank_mask:0xf bound_ctrl:1
	v_add_f32_dpp v25, v25, v25 quad_perm:[2,3,0,1] row_mask:0xf bank_mask:0xf bound_ctrl:1
	v_add_f32_dpp v26, v26, v26 quad_perm:[2,3,0,1] row_mask:0xf bank_mask:0xf bound_ctrl:1
	v_add_f32_dpp v27, v27, v27 quad_perm:[2,3,0,1] row_mask:0xf bank_mask:0xf bound_ctrl:1
	v_add_f32_dpp v28, v28, v28 quad_perm:[2,3,0,1] row_mask:0xf bank_mask:0xf bound_ctrl:1
	v_add_f32_dpp v29, v29, v29 quad_perm:[2,3,0,1] row_mask:0xf bank_mask:0xf bound_ctrl:1
	v_add_f32_dpp v30, v30, v30 quad_perm:[2,3,0,1] row_mask:0xf bank_mask:0xf bound_ctrl:1
	v_add_f32_dpp v31, v31, v31 quad_perm:[2,3,0,1] row_mask:0xf bank_mask:0xf bound_ctrl:1
	v_add_f32_dpp v24, v24, v24 row_half_mirror row_mask:0xf bank_mask:0xf bound_ctrl:1
	v_add_f32_dpp v25, v25, v25 row_half_mirror row_mask:0xf bank_mask:0xf bound_ctrl:1
	v_add_f32_dpp v26, v26, v26 row_half_mirror row_mask:0xf bank_mask:0xf bound_ctrl:1
	v_add_f32_dpp v27, v27, v27 row_half_mirror row_mask:0xf bank_mask:0xf bound_ctrl:1
	v_add_f32_dpp v28, v28, v28 row_half_mirror row_mask:0xf bank_mask:0xf bound_ctrl:1
	v_add_f32_dpp v29, v29, v29 row_half_mirror row_mask:0xf bank_mask:0xf bound_ctrl:1
	v_add_f32_dpp v30, v30, v30 row_half_mirror row_mask:0xf bank_mask:0xf bound_ctrl:1
	v_add_f32_dpp v31, v31, v31 row_half_mirror row_mask:0xf bank_mask:0xf bound_ctrl:1
	v_fma_f32 v24, v16, s91, -v24
	v_fma_f32 v25, v17, s91, -v25
	v_fma_f32 v26, v18, s91, -v26
	v_fma_f32 v27, v19, s91, -v27
	v_fma_f32 v28, v20, s91, -v28
	v_fma_f32 v29, v21, s91, -v29
	v_fma_f32 v30, v22, s91, -v30
	v_fma_f32 v31, v23, s91, -v31
	s_waitcnt lgkmcnt(0)
	v_mov_b32_e32 v15, v24
	v_cndmask_b32_e64 v15, v15, v25, s[6:7]
	v_cndmask_b32_e64 v15, v15, v26, s[68:69]
	v_cndmask_b32_e64 v15, v15, v27, s[92:93]
	v_cndmask_b32_e64 v15, v15, v28, s[94:95]
	v_cndmask_b32_e64 v15, v15, v29, s[96:97]
	v_cndmask_b32_e64 v15, v15, v30, s[98:99]
	v_cndmask_b32_e64 v15, v15, v31, s[100:101]
	s_nop 1
	v_mov_b32_dpp v41, v15 quad_perm:[0,0,0,0] row_mask:0xf bank_mask:0xf
	s_nop 1
	v_mov_b32_dpp v41, v41 row_half_mirror row_mask:0xf bank_mask:0xa
	v_fma_f32 v15, -v32, v41, v15
	s_nop 1
	v_mov_b32_dpp v41, v15 quad_perm:[1,1,1,1] row_mask:0xf bank_mask:0xf
	s_nop 1
	v_mov_b32_dpp v41, v41 row_half_mirror row_mask:0xf bank_mask:0xa
	v_fma_f32 v15, -v33, v41, v15
	s_nop 1
	v_mov_b32_dpp v41, v15 quad_perm:[2,2,2,2] row_mask:0xf bank_mask:0xf
	s_nop 1
	v_mov_b32_dpp v41, v41 row_half_mirror row_mask:0xf bank_mask:0xa
	v_fma_f32 v15, -v34, v41, v15
	s_nop 1
	v_mov_b32_dpp v41, v15 quad_perm:[3,3,3,3] row_mask:0xf bank_mask:0xf
	s_nop 1
	v_mov_b32_dpp v41, v41 row_half_mirror row_mask:0xf bank_mask:0xa
	v_fma_f32 v15, -v35, v41, v15
	s_nop 1
	v_mov_b32_dpp v41, v15 quad_perm:[0,0,0,0] row_mask:0xf bank_mask:0xf
	v_fma_f32 v15, -v36, v41, v15
	s_nop 1
	v_mov_b32_dpp v41, v15 quad_perm:[1,1,1,1] row_mask:0xf bank_mask:0xf
	v_fma_f32 v15, -v37, v41, v15
	s_nop 1
	v_mov_b32_dpp v41, v15 quad_perm:[2,2,2,2] row_mask:0xf bank_mask:0xf
	v_fma_f32 v15, -v38, v41, v15
	v_mul_f32_e32 v128, v4, v15
	v_mul_f32_e32 v129, v5, v15
	v_cvt_pk_bf16_f32 v128, v128, v128
	v_cvt_pk_bf16_f32 v129, v129, v129
	ds_write_b16 v2, v128 offset:8064
	ds_write_b16 v3, v129 offset:8064
	s_mov_b32 s91, 0
	s_setprio 0
	s_branch .LBB0_378
